# v13: v12 + attention unmasked-tile path fuses second-half exp with first-half PV MFMAs (in-wave MFMA/VALU overlap)
# baseline (speedup 1.0000x reference)
; __device__ __forceinline__ void phase_attn(const Frame& F, int l, bool last, int ai, int na) {
;     ...
;         for (int t = 0; t < ntile; ++t) {
;             const int bo = (t & 1) * AT_BUF;
;             __syncthreads();
;             if (t + 1 < ntile) { AT_STORE(AT_BUF - bo); if (t + 2 < ntile) AT_LOAD(t + 2); }
;             const int kpos0 = wlo + t * 64, q0w = qb * 128 + (w & 3) * 32;
;             const bool win = (t < nwin) && !(kpos0 <= q0w + 65 && kpos0 >= q0w - 97);
;             if ((t < nwin) && (kpos0 > q0w + 159 || kpos0 < q0w - 191)) continue;
.Lattn_tile_end:
	s_add_i32 s38, s38, 64
	s_add_i32 s39, s39, 1
	s_cmp_eq_u32 s28, s39
	s_cbranch_scc0 .LBB0_619
	s_branch .LBB0_602

; #define LAS __attribute__((address_space(3)))
; __device__ __forceinline__ void phase_attn(const Frame& F, int l, bool last, int ai, int na) {
;     ...
;             float mx = -1e30f;
; #pragma unroll
;             for (int kt = 0; kt < 2; ++kt)
; #pragma unroll
;                 for (int e = 0; e < 16; ++e) {
;                     if (win) { const int kp = kpos0 + kt * 32 + (e & 3) + 8 * (e >> 2) + 4 * hh; const int dd = kp - qpos; if (dd > 128 || dd < -128) sacc[kt][e] = -1e30f; }
;                     mx = fmaxf(mx, sacc[kt][e]); }
;             mx = fmaxf(mx, __shfl_xor(mx, 32));
;             const bool upd = mx > mrun + 8.0f;
;             const bool anyupd = __builtin_amdgcn_ballot_w64(upd) != 0ull;
;             const float mnew = upd ? mx : mrun;
;             float rs = 0.f;
; #pragma unroll
;             for (int kt = 0; kt < 2; ++kt)
; #pragma unroll
;                 for (int g4 = 0; g4 < 4; ++g4) { float pv4[4];
; #pragma unroll
;                     for (int e = 0; e < 4; ++e) { pv4[e] = __builtin_amdgcn_exp2f(sacc[kt][g4 * 4 + e] - mnew); rs += pv4[e]; }
;                     *(LAS u32x2*)(Pw + (r32 * 72 + kt * 32 + g4 * 8 + hh * 4) * 2) = (u32x2){pk_f16(pv4[0], pv4[1]), pk_f16(pv4[2], pv4[3])}; }
;             rs += __shfl_xor(rs, 32);
;             if (anyupd) { const float alpha = __builtin_amdgcn_exp2f(mrun - mnew); lrun *= alpha;
; #pragma unroll
;                 for (int dt = 0; dt < 4; ++dt)
; #pragma unroll
;                     for (int e = 0; e < 16; ++e) oacc[dt][e] *= alpha; }
.Lattn_nomask:
	s_nop 8
	v_max3_f32 v4, v96, s3, v97
	v_max3_f32 v4, v4, v98, v99
	v_max3_f32 v4, v4, v100, v101
	v_max3_f32 v4, v4, v102, v103
	v_max3_f32 v4, v4, v104, v105
	v_max3_f32 v4, v4, v106, v107
	v_max3_f32 v4, v4, v108, v109
	v_max3_f32 v4, v4, v110, v111
	v_max3_f32 v4, v4, v80, v81
	v_max3_f32 v4, v4, v82, v83
	v_max3_f32 v4, v4, v84, v85
	v_max3_f32 v4, v4, v86, v87
	v_max3_f32 v4, v4, v88, v89
	v_max3_f32 v4, v4, v90, v91
	v_max3_f32 v4, v4, v92, v93
	v_max3_f32 v0, v4, v94, v95
	ds_bpermute_b32 v4, v232, v0
	s_waitcnt lgkmcnt(0)
	v_max_f32_e32 v4, v4, v4
	v_max_f32_e32 v0, v0, v4
	v_add_f32_e32 v4, 0x41000000, v230
	v_cmp_gt_f32_e32 vcc, v0, v4
	s_nop 1
	v_cndmask_b32_e32 v0, v230, v0, vcc
	v_add_u32_e32 v12, s12, v191
	v_add_u32_e32 v13, s2, v191
	v_mov_b32_e32 v14, 0
	s_nop 1
	s_cbranch_vccz .Lnm_norescale
	v_sub_f32_e32 v4, v230, v0
	v_exp_f32_e32 v4, v4
	s_nop 0
	v_pk_mul_f32 v[78:79], v[78:79], v[4:5] op_sel_hi:[1,0]
	v_pk_mul_f32 v[76:77], v[76:77], v[4:5] op_sel_hi:[1,0]
	v_pk_mul_f32 v[74:75], v[74:75], v[4:5] op_sel_hi:[1,0]
	v_pk_mul_f32 v[72:73], v[72:73], v[4:5] op_sel_hi:[1,0]
	v_pk_mul_f32 v[70:71], v[70:71], v[4:5] op_sel_hi:[1,0]
	v_pk_mul_f32 v[68:69], v[68:69], v[4:5] op_sel_hi:[1,0]
	v_pk_mul_f32 v[66:67], v[66:67], v[4:5] op_sel_hi:[1,0]
	v_pk_mul_f32 v[64:65], v[64:65], v[4:5] op_sel_hi:[1,0]
	v_pk_mul_f32 v[62:63], v[62:63], v[4:5] op_sel_hi:[1,0]
	v_pk_mul_f32 v[60:61], v[60:61], v[4:5] op_sel_hi:[1,0]
	v_pk_mul_f32 v[58:59], v[58:59], v[4:5] op_sel_hi:[1,0]
	v_pk_mul_f32 v[56:57], v[56:57], v[4:5] op_sel_hi:[1,0]
	v_pk_mul_f32 v[54:55], v[54:55], v[4:5] op_sel_hi:[1,0]
	v_pk_mul_f32 v[52:53], v[52:53], v[4:5] op_sel_hi:[1,0]
	v_pk_mul_f32 v[50:51], v[50:51], v[4:5] op_sel_hi:[1,0]
	v_pk_mul_f32 v[48:49], v[48:49], v[4:5] op_sel_hi:[1,0]
	v_pk_mul_f32 v[46:47], v[46:47], v[4:5] op_sel_hi:[1,0]
	v_pk_mul_f32 v[44:45], v[44:45], v[4:5] op_sel_hi:[1,0]
	v_pk_mul_f32 v[42:43], v[42:43], v[4:5] op_sel_hi:[1,0]
	v_pk_mul_f32 v[40:41], v[40:41], v[4:5] op_sel_hi:[1,0]
	v_pk_mul_f32 v[38:39], v[38:39], v[4:5] op_sel_hi:[1,0]
	v_pk_mul_f32 v[36:37], v[36:37], v[4:5] op_sel_hi:[1,0]
	v_pk_mul_f32 v[34:35], v[34:35], v[4:5] op_sel_hi:[1,0]
	v_pk_mul_f32 v[32:33], v[32:33], v[4:5] op_sel_hi:[1,0]
	v_pk_mul_f32 v[30:31], v[30:31], v[4:5] op_sel_hi:[1,0]
	v_pk_mul_f32 v[28:29], v[28:29], v[4:5] op_sel_hi:[1,0]
	v_pk_mul_f32 v[26:27], v[26:27], v[4:5] op_sel_hi:[1,0]
	v_pk_mul_f32 v[24:25], v[24:25], v[4:5] op_sel_hi:[1,0]
	v_pk_mul_f32 v[22:23], v[22:23], v[4:5] op_sel_hi:[1,0]
	v_pk_mul_f32 v[20:21], v[20:21], v[4:5] op_sel_hi:[1,0]
	v_pk_mul_f32 v[18:19], v[18:19], v[4:5] op_sel_hi:[1,0]
	v_pk_mul_f32 v[16:17], v[16:17], v[4:5] op_sel_hi:[1,0]
	v_mul_f32_e32 v171, v171, v4
; #define LAS __attribute__((address_space(3)))
; __device__ __forceinline__ void phase_attn(const Frame& F, int l, bool last, int ai, int na) {
;     ...
;             float rs = 0.f;
; #pragma unroll
;             for (int kt = 0; kt < 2; ++kt)
; #pragma unroll
;                 for (int g4 = 0; g4 < 4; ++g4) { float pv4[4];
; #pragma unroll
;                     for (int e = 0; e < 4; ++e) { pv4[e] = __builtin_amdgcn_exp2f(sacc[kt][g4 * 4 + e] - mnew); rs += pv4[e]; }
;                     *(LAS u32x2*)(Pw + (r32 * 72 + kt * 32 + g4 * 8 + hh * 4) * 2) = (u32x2){pk_f16(pv4[0], pv4[1]), pk_f16(pv4[2], pv4[3])}; }
;             rs += __shfl_xor(rs, 32);
;             if (anyupd) { const float alpha = __builtin_amdgcn_exp2f(mrun - mnew); lrun *= alpha;
; #pragma unroll
;                 for (int dt = 0; dt < 4; ++dt)
; #pragma unroll
;                     for (int e = 0; e < 16; ++e) oacc[dt][e] *= alpha; }
;             lrun += rs; mrun = mnew;
;             asm volatile("s_waitcnt lgkmcnt(0)" ::: "memory");
; #pragma unroll
;             for (int s = 0; s < 4; ++s) { const f16x8 pb = *(const LAS f16x8*)(Pw + (r32 * 72 + s * 16 + hh * 8) * 2);
; #pragma unroll
;                 for (int dt = 0; dt < 4; ++dt) { const f16x8 a = *(const LAS f16x8*)(lds + bo + AT_V + ((dt * 32 + r32) * 72 + s * 16 + hh * 8) * 2);
;                     oacc[dt] = __builtin_amdgcn_mfma_f32_32x32x16_f16(a, pb, oacc[dt], 0, 0, 0); } }
.Lnm_norescale:
	v_sub_f32_e32 v6, v96, v0
	v_exp_f32_e32 v6, v6
	v_sub_f32_e32 v7, v97, v0
	v_exp_f32_e32 v7, v7
	v_sub_f32_e32 v8, v98, v0
	v_exp_f32_e32 v8, v8
	v_sub_f32_e32 v9, v99, v0
	v_exp_f32_e32 v9, v9
	v_add_f32_e32 v14, v14, v6
	v_add_f32_e32 v14, v14, v7
	v_add_f32_e32 v14, v14, v8
	v_add_f32_e32 v14, v14, v9
	v_cvt_pk_f16_f32 v2, v6, v7
	v_cvt_pk_f16_f32 v3, v8, v9
	v_sub_f32_e32 v6, v100, v0
	v_exp_f32_e32 v6, v6
	v_sub_f32_e32 v7, v101, v0
	v_exp_f32_e32 v7, v7
	v_sub_f32_e32 v8, v102, v0
	v_exp_f32_e32 v8, v8
	v_sub_f32_e32 v9, v103, v0
	v_exp_f32_e32 v9, v9
	v_add_f32_e32 v14, v14, v6
	v_add_f32_e32 v14, v14, v7
	v_add_f32_e32 v14, v14, v8
	v_add_f32_e32 v14, v14, v9
	v_cvt_pk_f16_f32 v4, v6, v7
	v_cvt_pk_f16_f32 v5, v8, v9
	ds_write2_b64 v228, v[2:3], v[4:5] offset1:2
	v_sub_f32_e32 v6, v104, v0
	v_exp_f32_e32 v6, v6
	v_sub_f32_e32 v7, v105, v0
	v_exp_f32_e32 v7, v7
	v_sub_f32_e32 v8, v106, v0
	v_exp_f32_e32 v8, v8
	v_sub_f32_e32 v9, v107, v0
	v_exp_f32_e32 v9, v9
	v_add_f32_e32 v14, v14, v6
	v_add_f32_e32 v14, v14, v7
	v_add_f32_e32 v14, v14, v8
	v_add_f32_e32 v14, v14, v9
	v_cvt_pk_f16_f32 v2, v6, v7
	v_cvt_pk_f16_f32 v3, v8, v9
	v_sub_f32_e32 v6, v108, v0
	v_exp_f32_e32 v6, v6
	v_sub_f32_e32 v7, v109, v0
	v_exp_f32_e32 v7, v7
	v_sub_f32_e32 v8, v110, v0
	v_exp_f32_e32 v8, v8
	v_sub_f32_e32 v9, v111, v0
	v_exp_f32_e32 v9, v9
	v_add_f32_e32 v14, v14, v6
	v_add_f32_e32 v14, v14, v7
	v_add_f32_e32 v14, v14, v8
	v_add_f32_e32 v14, v14, v9
	v_cvt_pk_f16_f32 v4, v6, v7
	v_cvt_pk_f16_f32 v5, v8, v9
	ds_write2_b64 v228, v[2:3], v[4:5] offset0:4 offset1:6
	ds_read_b128 v[200:203], v12
	ds_read_b128 v[242:245], v12 offset:32
	ds_read_b128 v[96:99], v13 offset:17408
	ds_read_b128 v[100:103], v13 offset:22016
	ds_read_b128 v[104:107], v13 offset:26624
	ds_read_b128 v[108:111], v13 offset:31232
	v_sub_f32_e32 v6, v80, v0
	v_exp_f32_e32 v6, v6
	v_sub_f32_e32 v7, v81, v0
	v_exp_f32_e32 v7, v7
	v_sub_f32_e32 v8, v82, v0
	v_exp_f32_e32 v8, v8
	v_sub_f32_e32 v9, v83, v0
	s_waitcnt lgkmcnt(3)
	v_mfma_f32_32x32x16_f16 v[64:79], v[96:99], v[200:203], v[64:79]
	ds_read_b128 v[96:99], v13 offset:17440
	v_exp_f32_e32 v9, v9
	v_add_f32_e32 v14, v14, v6
	v_add_f32_e32 v14, v14, v7
	v_add_f32_e32 v14, v14, v8
	v_add_f32_e32 v14, v14, v9
	v_cvt_pk_f16_f32 v2, v6, v7
	v_cvt_pk_f16_f32 v3, v8, v9
	s_waitcnt lgkmcnt(3)
	v_mfma_f32_32x32x16_f16 v[48:63], v[100:103], v[200:203], v[48:63]
	ds_read_b128 v[100:103], v13 offset:22048
	v_sub_f32_e32 v6, v84, v0
	v_exp_f32_e32 v6, v6
	v_sub_f32_e32 v7, v85, v0
	v_exp_f32_e32 v7, v7
	v_sub_f32_e32 v8, v86, v0
	v_exp_f32_e32 v8, v8
	v_sub_f32_e32 v9, v87, v0
	s_waitcnt lgkmcnt(3)
	v_mfma_f32_32x32x16_f16 v[32:47], v[104:107], v[200:203], v[32:47]
	ds_read_b128 v[104:107], v13 offset:26656
	v_exp_f32_e32 v9, v9
	v_add_f32_e32 v14, v14, v6
	v_add_f32_e32 v14, v14, v7
	v_add_f32_e32 v14, v14, v8
	v_add_f32_e32 v14, v14, v9
	v_cvt_pk_f16_f32 v4, v6, v7
	v_cvt_pk_f16_f32 v5, v8, v9
	ds_write2_b64 v228, v[2:3], v[4:5] offset0:8 offset1:10
	s_waitcnt lgkmcnt(4)
	v_mfma_f32_32x32x16_f16 v[16:31], v[108:111], v[200:203], v[16:31]
	ds_read_b128 v[108:111], v13 offset:31264
	v_sub_f32_e32 v6, v88, v0
	v_exp_f32_e32 v6, v6
	v_sub_f32_e32 v7, v89, v0
	v_exp_f32_e32 v7, v7
	v_sub_f32_e32 v8, v90, v0
	v_exp_f32_e32 v8, v8
	v_sub_f32_e32 v9, v91, v0
	s_waitcnt lgkmcnt(4)
	v_mfma_f32_32x32x16_f16 v[64:79], v[96:99], v[242:245], v[64:79]
	v_exp_f32_e32 v9, v9
	v_add_f32_e32 v14, v14, v6
	v_add_f32_e32 v14, v14, v7
	v_add_f32_e32 v14, v14, v8
	v_add_f32_e32 v14, v14, v9
	v_cvt_pk_f16_f32 v2, v6, v7
	v_cvt_pk_f16_f32 v3, v8, v9
	s_waitcnt lgkmcnt(3)
	v_mfma_f32_32x32x16_f16 v[48:63], v[100:103], v[242:245], v[48:63]
	v_sub_f32_e32 v6, v92, v0
	v_exp_f32_e32 v6, v6
	v_sub_f32_e32 v7, v93, v0
	v_exp_f32_e32 v7, v7
	v_sub_f32_e32 v8, v94, v0
	v_exp_f32_e32 v8, v8
	v_sub_f32_e32 v9, v95, v0
	s_waitcnt lgkmcnt(2)
	v_mfma_f32_32x32x16_f16 v[32:47], v[104:107], v[242:245], v[32:47]
	v_exp_f32_e32 v9, v9
	v_add_f32_e32 v14, v14, v6
	v_add_f32_e32 v14, v14, v7
	v_add_f32_e32 v14, v14, v8
	v_add_f32_e32 v14, v14, v9
	v_cvt_pk_f16_f32 v4, v6, v7
	v_cvt_pk_f16_f32 v5, v8, v9
	ds_write2_b64 v228, v[2:3], v[4:5] offset0:12 offset1:14
	ds_bpermute_b32 v15, v232, v14
	s_waitcnt lgkmcnt(2)
	v_mfma_f32_32x32x16_f16 v[16:31], v[108:111], v[242:245], v[16:31]
	ds_read_b128 v[246:249], v12 offset:64
	ds_read_b128 v[8:11], v12 offset:96
	ds_read_b128 v[80:83], v13 offset:17472
	ds_read_b128 v[84:87], v13 offset:22080
	ds_read_b128 v[88:91], v13 offset:26688
	ds_read_b128 v[92:95], v13 offset:31296
	ds_read_b128 v[96:99], v13 offset:17504
	ds_read_b128 v[100:103], v13 offset:22112
	ds_read_b128 v[104:107], v13 offset:26720
	ds_read_b128 v[108:111], v13 offset:31328
	s_waitcnt lgkmcnt(10)
	v_add_f32_e32 v14, v14, v15
	v_add_f32_e32 v171, v14, v171
	s_waitcnt lgkmcnt(7)
	v_mfma_f32_32x32x16_f16 v[64:79], v[80:83], v[246:249], v[64:79]
	s_waitcnt lgkmcnt(6)
	v_mfma_f32_32x32x16_f16 v[48:63], v[84:87], v[246:249], v[48:63]
	s_waitcnt lgkmcnt(5)
	v_mfma_f32_32x32x16_f16 v[32:47], v[88:91], v[246:249], v[32:47]
	s_waitcnt lgkmcnt(4)
	v_mfma_f32_32x32x16_f16 v[16:31], v[92:95], v[246:249], v[16:31]
	s_waitcnt lgkmcnt(3)
	v_mfma_f32_32x32x16_f16 v[64:79], v[96:99], v[8:11], v[64:79]
	s_waitcnt lgkmcnt(2)
	v_mfma_f32_32x32x16_f16 v[48:63], v[100:103], v[8:11], v[48:63]
	s_waitcnt lgkmcnt(1)
	v_mfma_f32_32x32x16_f16 v[32:47], v[104:107], v[8:11], v[32:47]
	s_waitcnt lgkmcnt(0)
	v_mfma_f32_32x32x16_f16 v[16:31], v[108:111], v[8:11], v[16:31]
	s_branch .Lattn_tile_end
